# recurrence interval: the 256 compression units moved from workgroups 0..127 to the 96 workgroups that only had the gate GEMM (A path was critical per delay experiments)
# speedup vs baseline: 1.0053x; 1.0053x over previous
; #define LAS __attribute__((address_space(3)))
; #define KIN(i) (((const float* const*)__builtin_amdgcn_kernarg_segment_ptr())[(i)])
; #define KWS() (((unsigned char* const*)__builtin_amdgcn_kernarg_segment_ptr())[32])
; __device__ __forceinline__ int vpos(int k) { return (k & ~12) | ((k & 4) << 1) | ((k & 8) >> 1); }
; #define IDS() int tid = threadIdx.x; asm volatile("" : "+v"(tid)); const int lane = tid & 63, wave = __builtin_amdgcn_readfirstlane(tid >> 6), gw = vcu * NWAVES + wave; (void)lane; (void)wave; (void)gw
; __device__ __forceinline__ void nsa_prep2_phase(bf16* z, const float* qg, const float* kg, bf16* vst, bf16* vwt, LAS unsigned char* lds, int tid, int u0, int ustride) {
;     __syncthreads();
;     for (int unit = u0; unit < 256; unit += ustride) {
;         const int b = unit >> 5, tb = unit & 31; const size_t row0 = (size_t)b * SEQ + tb * 64;
;         { const int tok = tid >> 3, ch = tid & 7, pc = vpos(tok);
; __global__ void __launch_bounds__(NWAVES * 64, 2) fwd_kernel(Args a) {
;     ...
;     { IDS(); nsa_prep2_phase(Z, KIN(22) + l * 64, KIN(23) + l * 64, VST, VWT, lds, tid, (int)blockIdx.x < 128 ? (int)blockIdx.x : 256, 128); }
;     for (int rep_ = 0; rep_ < REP_CMP; ++rep_){ IDS(); nsa_compress3_phase(Z, (const bf16*)(KWS() + WS_PHIT) + (size_t)l * 2 * 64 * 2048, (const float*)(KWS() + WS_PEC) + l * 128, KIN(23) + l * 64, KCH, KCL, VCT, lds, tid, (int)blockIdx.x < 128 ? (int)blockIdx.x : 256, 128); }
.LBB0_685:
	v_mov_b32_e32 v1, v0
	s_load_dwordx4 s[8:11], s[56:57], 0xb0
	s_lshl_b32 s68, s58, 6
	s_lshl_b64 s[4:5], s[68:69], 2
	v_readlane_b32 s0, v253, 20
	v_readlane_b32 s1, v253, 21
	s_waitcnt lgkmcnt(0)
	s_add_u32 s10, s10, s4
	s_addc_u32 s11, s11, s5
	s_sub_i32 s30, s2, 0x80
	s_lshr_b32 s31, s30, 2
	s_sub_i32 s28, s30, s31
	s_add_i32 s28, s28, -1
	s_and_b64 vcc, exec, s[0:1]
	s_barrier
	s_cbranch_vccz .LBB0_691
	v_ashrrev_i32_e32 v32, 3, v1
	v_lshlrev_b32_e32 v2, 1, v32
	v_lshlrev_b32_e32 v6, 2, v32
	v_and_b32_e32 v5, 7, v1
	v_and_b32_e32 v6, 16, v6
	v_and_b32_e32 v2, 0xffffffe6, v2
	v_add3_u32 v2, 0, v6, v2
	v_and_b32_e32 v6, 8, v32
	v_mul_u32_u24_e32 v7, 0x480, v5
	v_add3_u32 v118, v2, v6, v7
	v_and_b32_e32 v2, 4, v1
	v_cmp_eq_u32_e32 vcc, 0, v2
	v_mov_b32_e32 v2, 0x2400
	s_add_u32 s14, s8, s4
	v_cndmask_b32_e32 v2, v2, v223, vcc
	s_movk_i32 s0, 0x400
	v_lshl_add_u64 v[6:7], s[76:77], 0, v[2:3]
	v_lshlrev_b32_e32 v2, 7, v1
	s_addc_u32 s15, s9, s5
	v_ashrrev_i32_e32 v33, 31, v32
	v_cmp_gt_i32_e64 s[8:9], s0, v1
	v_and_b32_e32 v2, 0x180, v2
	v_readlane_b32 s0, v252, 33
	v_lshl_add_u64 v[34:35], v[6:7], 0, v[2:3]
	v_lshlrev_b64 v[6:7], 12, v[32:33]
	v_readlane_b32 s1, v252, 34
	v_mul_lo_u32 v2, v32, s87
	v_lshlrev_b32_e32 v4, 3, v5
	v_lshl_add_u64 v[36:37], s[0:1], 0, v[6:7]
	v_readlane_b32 s0, v252, 35
	v_add_u32_e32 v8, 0, v2
	v_lshlrev_b32_e32 v2, 4, v5
	v_readlane_b32 s1, v252, 36
	v_lshlrev_b32_e32 v119, 6, v1
	v_lshl_add_u64 v[40:41], s[76:77], 0, v[2:3]
	v_lshl_add_u64 v[38:39], s[0:1], 0, v[6:7]
	v_add_u32_e32 v120, v8, v2
	v_lshlrev_b32_e32 v42, 1, v4
	s_mov_b32 s0, s2
	s_branch .LBB0_688

; #define LAS __attribute__((address_space(3)))
; __device__ __forceinline__ void nsa_compress3_phase(const bf16* z, const bf16* phit, const float* pec, const float* kg, bf16* kch, bf16* kcl, bf16* vct, LAS unsigned char* lds, int tid, int u0, int ustride) {
;     LAS float* part = (LAS float*)lds;
;     const int lane = tid & 63, wave = __builtin_amdgcn_readfirstlane(tid >> 6), r32 = lane & 31, hi = lane >> 5;
;     __syncthreads();
;     for (int unit = u0; unit < 256; unit += ustride) {
;         const int mt = unit & 3, kv = (unit >> 2) & 1, g = (unit >> 3) & 3, b = unit >> 5;
;         int n = 32 * mt + r32; n = n > NCMP - 1 ? NCMP - 1 : n;
;         const bf16* ap = z + ((size_t)b * SEQ + 16 * n) * ZP + (kv ? C_VC : C_KC) + g * 64 + 8 * hi;
;         const bf16* bp = phit + (size_t)kv * 64 * 2048 + (size_t)r32 * 2048 + 8 * hi;
;         f32x16 acc0, acc1;
; #pragma unroll
;         for (int r = 0; r < 16; ++r) { acc0[r] = 0.f; acc1[r] = 0.f; }
; #pragma unroll 4
;         for (int st = 0; st < 16; ++st) { const int sidx = wave * 16 + st, l = sidx >> 2, d0 = (sidx & 3) * 16;
.LBB0_691:
	s_and_b32 s4, s30, 3
	v_mov_b32_e32 v2, v0
	s_cmp_lg_u32 s4, 0
	s_cselect_b64 s[4:5], -1, 0
	s_cmp_lt_i32 s2, 0x80
	s_cselect_b64 s[4:5], 0, s[4:5]
	s_and_b64 vcc, exec, s[4:5]
	v_readfirstlane_b32 s0, v2
	s_barrier
	s_cbranch_vccz .LBB0_700
	s_lshl_b32 s68, s58, 7
	s_lshl_b64 s[4:5], s[58:59], 19
	s_lshl_b64 s[6:7], s[68:69], 2
	v_readlane_b32 s8, v252, 5
	v_readlane_b32 s9, v252, 6
	s_add_u32 s6, s8, s6
	s_addc_u32 s7, s9, s7
	s_ashr_i32 s1, s0, 6
	v_and_b32_e32 v1, 31, v2
	v_bfe_u32 v5, v2, 5, 1
	s_lshl_b32 s8, s1, 13
	v_lshlrev_b32_e32 v6, 10, v5
	s_add_i32 s8, s8, 0
	v_lshlrev_b32_e32 v7, 2, v1
	v_ashrrev_i32_e32 v53, 4, v2
	v_lshlrev_b32_e32 v2, 2, v2
	v_add3_u32 v52, s8, v6, v7
	v_and_b32_e32 v6, 60, v2
	v_lshlrev_b32_e32 v2, 2, v6
	v_lshl_add_u64 v[36:37], s[6:7], 0, v[2:3]
	v_lshlrev_b32_e32 v7, 8, v53
	v_readlane_b32 s6, v252, 27
	v_add3_u32 v54, 0, v7, v2
	v_lshl_add_u64 v[38:39], s[10:11], 0, v[2:3]
	v_lshlrev_b32_e32 v2, 1, v6
	v_readlane_b32 s7, v252, 28
	v_lshlrev_b32_e32 v4, 3, v5
	v_lshlrev_b32_e32 v5, 4, v5
	v_lshl_add_u64 v[40:41], s[6:7], 0, v[2:3]
	v_readlane_b32 s6, v252, 29
	v_readlane_b32 s7, v252, 30
	v_lshrrev_b32_e32 v7, 1, v53
	v_lshlrev_b32_e32 v44, 8, v6
	v_lshl_add_u64 v[42:43], s[6:7], 0, v[2:3]
	v_lshlrev_b32_e32 v2, 12, v1
	v_or3_b32 v6, s4, v2, v5
	s_lshl_b32 s4, s1, 8
	v_and_b32_e32 v55, 4, v7
	v_mov_b32_e32 v7, s5
	s_ashr_i32 s5, s4, 31
	s_lshl_b32 s0, s1, 4
	s_lshl_b64 s[4:5], s[4:5], 1
	s_add_u32 s4, s48, s4
	s_addc_u32 s5, s49, s5
	v_mov_b32_e32 v45, v3
	v_lshl_add_u64 v[46:47], s[4:5], 0, v[6:7]
	v_lshlrev_b32_e32 v2, 1, v4
	s_mov_b32 s1, s28
	s_branch .LBB0_694
.LBB0_693:
	s_add_i32 s4, s1, 0x60
	s_cmpk_lt_i32 s4, 0x100
	s_mov_b32 s1, s4
	s_barrier
	s_cbranch_scc0 .LBB0_700
